# plus: fp8 GEMM epilogue s_nop 15 x2 pads removed (accumulators of the last MFMA phase are read hundreds of instructions later)
# baseline (speedup 1.0000x reference)
.LBB0_966:
	v_pk_add_f32 v[6:7], v[32:33], v[164:165]
	v_pk_add_f32 v[14:15], v[40:41], v[168:169]
	v_min_f32_e32 v6, 0x40e00000, v6
	v_min_f32_e32 v7, 0x40e00000, v7
	v_pk_mul_f32 v[20:21], v[6:7], s[86:87] op_sel_hi:[1,0]
	v_pk_add_f32 v[4:5], v[34:35], v[166:167]
	v_exp_f32_e32 v20, v20
	v_exp_f32_e32 v21, v21
	v_med3_f32 v14, v14, s18, v236
	v_med3_f32 v15, v15, s18, v236
	v_pk_fma_f32 v[14:15], v[14:15], 4.0, 4.0 op_sel_hi:[1,0,0]
	v_pk_add_f32 v[20:21], v[20:21], 1.0 op_sel_hi:[1,0]
	v_min_f32_e32 v4, 0x40e00000, v4
	v_rcp_f32_e32 v20, v20
	v_rcp_f32_e32 v21, v21
	v_min_f32_e32 v5, 0x40e00000, v5
	v_pk_add_f32 v[10:11], v[36:37], v[160:161]
	v_pk_add_f32 v[8:9], v[38:39], v[162:163]
	v_pk_mul_f32 v[6:7], v[6:7], v[20:21]
	v_min_f32_e32 v10, 0x40e00000, v10
	v_pk_mul_f32 v[6:7], v[6:7], v[14:15]
	v_pk_mul_f32 v[14:15], v[4:5], s[86:87] op_sel_hi:[1,0]
	v_min_f32_e32 v11, 0x40e00000, v11
	v_exp_f32_e32 v14, v14
	v_exp_f32_e32 v15, v15
	v_min_f32_e32 v8, 0x40e00000, v8
	v_min_f32_e32 v9, 0x40e00000, v9
	v_pk_add_f32 v[12:13], v[42:43], v[170:171]
	v_pk_add_f32 v[14:15], v[14:15], 1.0 op_sel_hi:[1,0]
	v_med3_f32 v12, v12, s18, v236
	v_rcp_f32_e32 v14, v14
	v_rcp_f32_e32 v15, v15
	v_med3_f32 v13, v13, s18, v236
	v_pk_add_f32 v[18:19], v[44:45], v[172:173]
	v_pk_fma_f32 v[12:13], v[12:13], 4.0, 4.0 op_sel_hi:[1,0,0]
	v_pk_mul_f32 v[4:5], v[4:5], v[14:15]
	v_pk_mul_f32 v[14:15], v[10:11], s[86:87] op_sel_hi:[1,0]
	v_pk_mul_f32 v[4:5], v[4:5], v[12:13]
	v_exp_f32_e32 v14, v14
	v_exp_f32_e32 v15, v15
	v_med3_f32 v12, v18, s18, v236
	v_med3_f32 v13, v19, s18, v236
	v_pk_add_f32 v[16:17], v[46:47], v[174:175]
	v_pk_add_f32 v[14:15], v[14:15], 1.0 op_sel_hi:[1,0]
	v_pk_fma_f32 v[12:13], v[12:13], 4.0, 4.0 op_sel_hi:[1,0,0]
	v_rcp_f32_e32 v14, v14
	v_rcp_f32_e32 v15, v15
	v_add_u32_e32 v2, s8, v200
	v_ashrrev_i32_e32 v3, 31, v2
	v_or_b32_e32 v0, s36, v202
	v_pk_mul_f32 v[10:11], v[10:11], v[14:15]
	v_pk_mul_f32 v[14:15], v[8:9], s[86:87] op_sel_hi:[1,0]
	v_pk_mul_f32 v[10:11], v[10:11], v[12:13]
	v_exp_f32_e32 v14, v14
	v_exp_f32_e32 v15, v15
	v_med3_f32 v12, v16, s18, v236
	v_med3_f32 v13, v17, s18, v236
	v_pk_fma_f32 v[12:13], v[12:13], 4.0, 4.0 op_sel_hi:[1,0,0]
	v_pk_add_f32 v[14:15], v[14:15], 1.0 op_sel_hi:[1,0]
	v_lshlrev_b64 v[2:3], 10, v[2:3]
	v_rcp_f32_e32 v14, v14
	v_rcp_f32_e32 v15, v15
	v_ashrrev_i32_e32 v1, 31, v0
	v_lshl_add_u64 v[2:3], s[16:17], 0, v[2:3]
	v_lshl_add_u64 v[0:1], v[2:3], 0, v[0:1]
	v_pk_mul_f32 v[8:9], v[8:9], v[14:15]
	v_pk_add_f32 v[2:3], v[34:35], v[150:151]
	v_pk_mul_f32 v[8:9], v[8:9], v[12:13]
	v_mov_b32_e32 v12, v213
	v_cvt_pk_fp8_f32 v12, v6, v7
	v_mov_b32_e32 v13, v213
	v_cvt_pk_fp8_f32 v13, v10, v11
	v_min_f32_e32 v2, 0x40e00000, v2
	v_cvt_pk_fp8_f32 v12, v4, v5 op_sel:[0,0,1]
	v_pk_add_f32 v[4:5], v[32:33], v[148:149]
	v_cvt_pk_fp8_f32 v13, v8, v9 op_sel:[0,0,1]
	v_min_f32_e32 v4, 0x40e00000, v4
	v_min_f32_e32 v5, 0x40e00000, v5
	v_pk_mul_f32 v[18:19], v[4:5], s[86:87] op_sel_hi:[1,0]
	global_store_dwordx2 v[0:1], v[12:13], off
	v_exp_f32_e32 v18, v18
	v_exp_f32_e32 v19, v19
	v_pk_add_f32 v[12:13], v[40:41], v[156:157]
	v_min_f32_e32 v3, 0x40e00000, v3
	v_med3_f32 v12, v12, s18, v236
	v_pk_add_f32 v[18:19], v[18:19], 1.0 op_sel_hi:[1,0]
	v_med3_f32 v13, v13, s18, v236
	v_rcp_f32_e32 v18, v18
	v_rcp_f32_e32 v19, v19
	v_pk_fma_f32 v[12:13], v[12:13], 4.0, 4.0 op_sel_hi:[1,0,0]
	v_pk_add_f32 v[8:9], v[36:37], v[144:145]
	v_pk_add_f32 v[6:7], v[38:39], v[146:147]
	v_pk_mul_f32 v[4:5], v[4:5], v[18:19]
	v_min_f32_e32 v8, 0x40e00000, v8
	v_pk_mul_f32 v[4:5], v[4:5], v[12:13]
	v_pk_mul_f32 v[12:13], v[2:3], s[86:87] op_sel_hi:[1,0]
	v_min_f32_e32 v9, 0x40e00000, v9
	v_exp_f32_e32 v12, v12
	v_exp_f32_e32 v13, v13
	v_min_f32_e32 v6, 0x40e00000, v6
	v_min_f32_e32 v7, 0x40e00000, v7
	v_pk_add_f32 v[10:11], v[42:43], v[158:159]
	v_pk_add_f32 v[12:13], v[12:13], 1.0 op_sel_hi:[1,0]
	v_med3_f32 v10, v10, s18, v236
	v_rcp_f32_e32 v12, v12
	v_rcp_f32_e32 v13, v13
	v_med3_f32 v11, v11, s18, v236
	v_pk_add_f32 v[16:17], v[44:45], v[152:153]
	v_pk_fma_f32 v[10:11], v[10:11], 4.0, 4.0 op_sel_hi:[1,0,0]
	v_pk_mul_f32 v[2:3], v[2:3], v[12:13]
	v_pk_mul_f32 v[12:13], v[8:9], s[86:87] op_sel_hi:[1,0]
	v_pk_mul_f32 v[2:3], v[2:3], v[10:11]
	v_exp_f32_e32 v12, v12
	v_exp_f32_e32 v13, v13
	v_med3_f32 v10, v16, s18, v236
	v_med3_f32 v11, v17, s18, v236
	v_pk_add_f32 v[14:15], v[46:47], v[154:155]
	v_pk_add_f32 v[12:13], v[12:13], 1.0 op_sel_hi:[1,0]
	v_pk_fma_f32 v[10:11], v[10:11], 4.0, 4.0 op_sel_hi:[1,0,0]
	v_rcp_f32_e32 v12, v12
	v_rcp_f32_e32 v13, v13
	s_movk_i32 s8, 0x4000
	v_pk_add_f32 v[16:17], v[44:45], v[136:137]
	v_mov_b32_e32 v251, v230
	v_pk_mul_f32 v[8:9], v[8:9], v[12:13]
	v_pk_mul_f32 v[12:13], v[6:7], s[86:87] op_sel_hi:[1,0]
	v_pk_mul_f32 v[8:9], v[8:9], v[10:11]
	v_exp_f32_e32 v12, v12
	v_exp_f32_e32 v13, v13
	v_med3_f32 v10, v14, s18, v236
	v_med3_f32 v11, v15, s18, v236
	v_pk_fma_f32 v[10:11], v[10:11], 4.0, 4.0 op_sel_hi:[1,0,0]
	v_pk_add_f32 v[12:13], v[12:13], 1.0 op_sel_hi:[1,0]
	v_pk_add_f32 v[14:15], v[46:47], v[138:139]
	v_rcp_f32_e32 v12, v12
	v_rcp_f32_e32 v13, v13
	v_mov_b32_e32 v252, v231
	v_pk_mul_f32 v[6:7], v[6:7], v[12:13]
	s_nop 0
	v_pk_mul_f32 v[6:7], v[6:7], v[10:11]
	v_mov_b32_e32 v10, v213
	v_cvt_pk_fp8_f32 v10, v4, v5
	v_pk_add_f32 v[4:5], v[32:33], v[132:133]
	v_mov_b32_e32 v11, v213
	v_min_f32_e32 v4, 0x40e00000, v4
	v_min_f32_e32 v5, 0x40e00000, v5
	v_pk_mul_f32 v[18:19], v[4:5], s[86:87] op_sel_hi:[1,0]
	v_cvt_pk_fp8_f32 v11, v8, v9
	v_exp_f32_e32 v18, v18
	v_exp_f32_e32 v19, v19
	v_cvt_pk_fp8_f32 v10, v2, v3 op_sel:[0,0,1]
	v_cvt_pk_fp8_f32 v11, v6, v7 op_sel:[0,0,1]
	v_add_co_u32_e32 v2, vcc, s8, v0
	v_pk_add_f32 v[18:19], v[18:19], 1.0 op_sel_hi:[1,0]
	s_nop 0
	v_addc_co_u32_e32 v3, vcc, 0, v1, vcc
	v_rcp_f32_e32 v18, v18
	v_rcp_f32_e32 v19, v19
	v_pk_add_f32 v[12:13], v[40:41], v[140:141]
	global_store_dwordx2 v[2:3], v[10:11], off
	v_pk_add_f32 v[2:3], v[34:35], v[134:135]
	v_med3_f32 v12, v12, s18, v236
	v_med3_f32 v13, v13, s18, v236
	v_pk_mul_f32 v[4:5], v[4:5], v[18:19]
	v_pk_fma_f32 v[12:13], v[12:13], 4.0, 4.0 op_sel_hi:[1,0,0]
	v_min_f32_e32 v2, 0x40e00000, v2
	v_min_f32_e32 v3, 0x40e00000, v3
	v_pk_mul_f32 v[4:5], v[4:5], v[12:13]
	v_pk_mul_f32 v[12:13], v[2:3], s[86:87] op_sel_hi:[1,0]
	v_pk_add_f32 v[8:9], v[36:37], v[128:129]
	v_exp_f32_e32 v12, v12
	v_exp_f32_e32 v13, v13
	v_min_f32_e32 v8, 0x40e00000, v8
	v_min_f32_e32 v9, 0x40e00000, v9
	v_pk_add_f32 v[6:7], v[38:39], v[130:131]
	v_pk_add_f32 v[12:13], v[12:13], 1.0 op_sel_hi:[1,0]
	v_min_f32_e32 v6, 0x40e00000, v6
	v_rcp_f32_e32 v12, v12
	v_rcp_f32_e32 v13, v13
	v_min_f32_e32 v7, 0x40e00000, v7
	v_pk_add_f32 v[10:11], v[42:43], v[142:143]
	s_mov_b32 s8, 0xc000
	v_pk_mul_f32 v[2:3], v[2:3], v[12:13]
	v_pk_mul_f32 v[12:13], v[8:9], s[86:87] op_sel_hi:[1,0]
	v_med3_f32 v10, v10, s18, v236
	v_exp_f32_e32 v12, v12
	v_exp_f32_e32 v13, v13
	v_med3_f32 v11, v11, s18, v236
	v_pk_fma_f32 v[10:11], v[10:11], 4.0, 4.0 op_sel_hi:[1,0,0]
	v_pk_add_f32 v[12:13], v[12:13], 1.0 op_sel_hi:[1,0]
	s_nop 0
	v_rcp_f32_e32 v12, v12
	v_rcp_f32_e32 v13, v13
	v_pk_mul_f32 v[2:3], v[2:3], v[10:11]
	v_med3_f32 v10, v16, s18, v236
	v_med3_f32 v11, v17, s18, v236
	v_pk_mul_f32 v[8:9], v[8:9], v[12:13]
	v_pk_mul_f32 v[12:13], v[6:7], s[86:87] op_sel_hi:[1,0]
	v_pk_fma_f32 v[10:11], v[10:11], 4.0, 4.0 op_sel_hi:[1,0,0]
	v_exp_f32_e32 v12, v12
	v_exp_f32_e32 v13, v13
	v_pk_mul_f32 v[8:9], v[8:9], v[10:11]
	v_med3_f32 v10, v14, s18, v236
	v_med3_f32 v11, v15, s18, v236
	v_pk_add_f32 v[12:13], v[12:13], 1.0 op_sel_hi:[1,0]
	v_pk_fma_f32 v[10:11], v[10:11], 4.0, 4.0 op_sel_hi:[1,0,0]
	v_rcp_f32_e32 v12, v12
	v_rcp_f32_e32 v13, v13
	v_pk_add_f32 v[16:17], v[44:45], v[120:121]
	v_pk_add_f32 v[14:15], v[46:47], v[122:123]
	v_pk_mul_f32 v[6:7], v[6:7], v[12:13]
	s_nop 0
	v_pk_mul_f32 v[6:7], v[6:7], v[10:11]
	v_mov_b32_e32 v10, v213
	v_cvt_pk_fp8_f32 v10, v4, v5
	v_pk_add_f32 v[4:5], v[32:33], v[116:117]
	v_mov_b32_e32 v11, v213
	v_min_f32_e32 v4, 0x40e00000, v4
	v_min_f32_e32 v5, 0x40e00000, v5
	v_pk_mul_f32 v[18:19], v[4:5], s[86:87] op_sel_hi:[1,0]
	v_cvt_pk_fp8_f32 v11, v8, v9
	v_exp_f32_e32 v18, v18
	v_exp_f32_e32 v19, v19
	v_cvt_pk_fp8_f32 v10, v2, v3 op_sel:[0,0,1]
	v_cvt_pk_fp8_f32 v11, v6, v7 op_sel:[0,0,1]
	v_add_co_u32_e32 v2, vcc, s72, v0
	v_pk_add_f32 v[18:19], v[18:19], 1.0 op_sel_hi:[1,0]
	s_nop 0
	v_addc_co_u32_e32 v3, vcc, 0, v1, vcc
	v_rcp_f32_e32 v18, v18
	v_rcp_f32_e32 v19, v19
	v_pk_add_f32 v[12:13], v[40:41], v[124:125]
	global_store_dwordx2 v[2:3], v[10:11], off
	v_pk_add_f32 v[2:3], v[34:35], v[118:119]
	v_med3_f32 v12, v12, s18, v236
	v_med3_f32 v13, v13, s18, v236
	v_pk_mul_f32 v[4:5], v[4:5], v[18:19]
	v_pk_fma_f32 v[12:13], v[12:13], 4.0, 4.0 op_sel_hi:[1,0,0]
	v_min_f32_e32 v2, 0x40e00000, v2
	v_min_f32_e32 v3, 0x40e00000, v3
	v_pk_mul_f32 v[4:5], v[4:5], v[12:13]
	v_pk_mul_f32 v[12:13], v[2:3], s[86:87] op_sel_hi:[1,0]
	v_pk_add_f32 v[8:9], v[36:37], v[112:113]
	v_exp_f32_e32 v12, v12
	v_exp_f32_e32 v13, v13
	v_min_f32_e32 v8, 0x40e00000, v8
	v_min_f32_e32 v9, 0x40e00000, v9
	v_pk_add_f32 v[6:7], v[38:39], v[114:115]
	v_pk_add_f32 v[12:13], v[12:13], 1.0 op_sel_hi:[1,0]
	v_min_f32_e32 v6, 0x40e00000, v6
	v_rcp_f32_e32 v12, v12
	v_rcp_f32_e32 v13, v13
	v_min_f32_e32 v7, 0x40e00000, v7
	v_pk_add_f32 v[10:11], v[42:43], v[126:127]
	v_pk_mul_f32 v[2:3], v[2:3], v[12:13]
	v_pk_mul_f32 v[12:13], v[8:9], s[86:87] op_sel_hi:[1,0]
	v_med3_f32 v10, v10, s18, v236
	v_exp_f32_e32 v12, v12
	v_exp_f32_e32 v13, v13
	v_med3_f32 v11, v11, s18, v236
	v_pk_fma_f32 v[10:11], v[10:11], 4.0, 4.0 op_sel_hi:[1,0,0]
	v_pk_add_f32 v[12:13], v[12:13], 1.0 op_sel_hi:[1,0]
	s_nop 0
	v_rcp_f32_e32 v12, v12
	v_rcp_f32_e32 v13, v13
	v_pk_mul_f32 v[2:3], v[2:3], v[10:11]
	v_med3_f32 v10, v16, s18, v236
	v_med3_f32 v11, v17, s18, v236
	v_pk_mul_f32 v[8:9], v[8:9], v[12:13]
	v_pk_mul_f32 v[12:13], v[6:7], s[86:87] op_sel_hi:[1,0]
	v_pk_fma_f32 v[10:11], v[10:11], 4.0, 4.0 op_sel_hi:[1,0,0]
	v_exp_f32_e32 v12, v12
	v_exp_f32_e32 v13, v13
	v_pk_mul_f32 v[8:9], v[8:9], v[10:11]
	v_med3_f32 v10, v14, s18, v236
	v_med3_f32 v11, v15, s18, v236
	v_pk_add_f32 v[12:13], v[12:13], 1.0 op_sel_hi:[1,0]
	v_pk_fma_f32 v[10:11], v[10:11], 4.0, 4.0 op_sel_hi:[1,0,0]
	v_rcp_f32_e32 v12, v12
	v_rcp_f32_e32 v13, v13
	v_pk_add_f32 v[16:17], v[44:45], v[104:105]
	v_pk_add_f32 v[14:15], v[46:47], v[106:107]
	v_pk_mul_f32 v[6:7], v[6:7], v[12:13]
	s_nop 0
	v_pk_mul_f32 v[6:7], v[6:7], v[10:11]
	v_mov_b32_e32 v10, v213
	v_cvt_pk_fp8_f32 v10, v4, v5
	v_pk_add_f32 v[4:5], v[32:33], v[100:101]
	v_mov_b32_e32 v11, v213
	v_min_f32_e32 v4, 0x40e00000, v4
	v_min_f32_e32 v5, 0x40e00000, v5
	v_pk_mul_f32 v[18:19], v[4:5], s[86:87] op_sel_hi:[1,0]
	v_cvt_pk_fp8_f32 v11, v8, v9
	v_exp_f32_e32 v18, v18
	v_exp_f32_e32 v19, v19
	v_cvt_pk_fp8_f32 v10, v2, v3 op_sel:[0,0,1]
	v_cvt_pk_fp8_f32 v11, v6, v7 op_sel:[0,0,1]
	v_add_co_u32_e32 v2, vcc, s8, v0
	v_pk_add_f32 v[18:19], v[18:19], 1.0 op_sel_hi:[1,0]
	s_nop 0
	v_addc_co_u32_e32 v3, vcc, 0, v1, vcc
	v_rcp_f32_e32 v18, v18
	v_rcp_f32_e32 v19, v19
	v_pk_add_f32 v[12:13], v[40:41], v[108:109]
	global_store_dwordx2 v[2:3], v[10:11], off
	v_pk_add_f32 v[2:3], v[34:35], v[102:103]
	v_med3_f32 v12, v12, s18, v236
	v_med3_f32 v13, v13, s18, v236
	v_pk_mul_f32 v[4:5], v[4:5], v[18:19]
	v_pk_fma_f32 v[12:13], v[12:13], 4.0, 4.0 op_sel_hi:[1,0,0]
	v_min_f32_e32 v2, 0x40e00000, v2
	v_min_f32_e32 v3, 0x40e00000, v3
	v_pk_mul_f32 v[4:5], v[4:5], v[12:13]
	v_pk_mul_f32 v[12:13], v[2:3], s[86:87] op_sel_hi:[1,0]
	v_pk_add_f32 v[8:9], v[36:37], v[96:97]
	v_exp_f32_e32 v12, v12
	v_exp_f32_e32 v13, v13
	v_min_f32_e32 v8, 0x40e00000, v8
	v_min_f32_e32 v9, 0x40e00000, v9
	v_pk_add_f32 v[6:7], v[38:39], v[98:99]
	v_pk_add_f32 v[12:13], v[12:13], 1.0 op_sel_hi:[1,0]
	v_min_f32_e32 v6, 0x40e00000, v6
	v_rcp_f32_e32 v12, v12
	v_rcp_f32_e32 v13, v13
	v_min_f32_e32 v7, 0x40e00000, v7
	v_pk_add_f32 v[10:11], v[42:43], v[110:111]
	s_mov_b32 s8, 0x24000
	v_pk_mul_f32 v[2:3], v[2:3], v[12:13]
	v_pk_mul_f32 v[12:13], v[8:9], s[86:87] op_sel_hi:[1,0]
	v_med3_f32 v10, v10, s18, v236
	v_exp_f32_e32 v12, v12
	v_exp_f32_e32 v13, v13
	v_med3_f32 v11, v11, s18, v236
	v_pk_fma_f32 v[10:11], v[10:11], 4.0, 4.0 op_sel_hi:[1,0,0]
	v_pk_add_f32 v[12:13], v[12:13], 1.0 op_sel_hi:[1,0]
	s_nop 0
	v_rcp_f32_e32 v12, v12
	v_rcp_f32_e32 v13, v13
	v_pk_mul_f32 v[2:3], v[2:3], v[10:11]
	v_med3_f32 v10, v16, s18, v236
	v_med3_f32 v11, v17, s18, v236
	v_pk_mul_f32 v[8:9], v[8:9], v[12:13]
	v_pk_mul_f32 v[12:13], v[6:7], s[86:87] op_sel_hi:[1,0]
	v_pk_fma_f32 v[10:11], v[10:11], 4.0, 4.0 op_sel_hi:[1,0,0]
	v_exp_f32_e32 v12, v12
	v_exp_f32_e32 v13, v13
	v_pk_mul_f32 v[8:9], v[8:9], v[10:11]
	v_med3_f32 v10, v14, s18, v236
	v_med3_f32 v11, v15, s18, v236
	v_pk_add_f32 v[12:13], v[12:13], 1.0 op_sel_hi:[1,0]
	v_pk_fma_f32 v[10:11], v[10:11], 4.0, 4.0 op_sel_hi:[1,0,0]
	v_rcp_f32_e32 v12, v12
	v_rcp_f32_e32 v13, v13
	v_pk_add_f32 v[16:17], v[44:45], v[88:89]
	v_pk_add_f32 v[14:15], v[46:47], v[90:91]
	v_pk_mul_f32 v[6:7], v[6:7], v[12:13]
	s_nop 0
	v_pk_mul_f32 v[6:7], v[6:7], v[10:11]
	v_mov_b32_e32 v10, v213
	v_cvt_pk_fp8_f32 v10, v4, v5
	v_pk_add_f32 v[4:5], v[32:33], v[84:85]
	v_mov_b32_e32 v11, v213
	v_min_f32_e32 v4, 0x40e00000, v4
	v_min_f32_e32 v5, 0x40e00000, v5
	v_pk_mul_f32 v[18:19], v[4:5], s[86:87] op_sel_hi:[1,0]
	v_cvt_pk_fp8_f32 v11, v8, v9
	v_exp_f32_e32 v18, v18
	v_exp_f32_e32 v19, v19
	v_cvt_pk_fp8_f32 v10, v2, v3 op_sel:[0,0,1]
	v_cvt_pk_fp8_f32 v11, v6, v7 op_sel:[0,0,1]
	v_add_co_u32_e32 v2, vcc, s74, v0
	v_pk_add_f32 v[18:19], v[18:19], 1.0 op_sel_hi:[1,0]
	s_nop 0
	v_addc_co_u32_e32 v3, vcc, 0, v1, vcc
	v_rcp_f32_e32 v18, v18
	v_rcp_f32_e32 v19, v19
	v_pk_add_f32 v[12:13], v[40:41], v[92:93]
	global_store_dwordx2 v[2:3], v[10:11], off
	v_pk_add_f32 v[2:3], v[34:35], v[86:87]
	v_med3_f32 v12, v12, s18, v236
	v_med3_f32 v13, v13, s18, v236
	v_pk_mul_f32 v[4:5], v[4:5], v[18:19]
	v_pk_fma_f32 v[12:13], v[12:13], 4.0, 4.0 op_sel_hi:[1,0,0]
	v_min_f32_e32 v2, 0x40e00000, v2
	v_min_f32_e32 v3, 0x40e00000, v3
	v_pk_mul_f32 v[4:5], v[4:5], v[12:13]
	v_pk_mul_f32 v[12:13], v[2:3], s[86:87] op_sel_hi:[1,0]
	v_pk_add_f32 v[8:9], v[36:37], v[80:81]
	v_exp_f32_e32 v12, v12
	v_exp_f32_e32 v13, v13
	v_min_f32_e32 v8, 0x40e00000, v8
	v_min_f32_e32 v9, 0x40e00000, v9
	v_pk_add_f32 v[6:7], v[38:39], v[82:83]
	v_pk_add_f32 v[12:13], v[12:13], 1.0 op_sel_hi:[1,0]
	v_min_f32_e32 v6, 0x40e00000, v6
	v_rcp_f32_e32 v12, v12
	v_rcp_f32_e32 v13, v13
	v_min_f32_e32 v7, 0x40e00000, v7
	v_pk_add_f32 v[10:11], v[42:43], v[94:95]
	v_pk_mul_f32 v[2:3], v[2:3], v[12:13]
	v_pk_mul_f32 v[12:13], v[8:9], s[86:87] op_sel_hi:[1,0]
	v_med3_f32 v10, v10, s18, v236
	v_exp_f32_e32 v12, v12
	v_exp_f32_e32 v13, v13
	v_med3_f32 v11, v11, s18, v236
	v_pk_fma_f32 v[10:11], v[10:11], 4.0, 4.0 op_sel_hi:[1,0,0]
	v_pk_add_f32 v[12:13], v[12:13], 1.0 op_sel_hi:[1,0]
	s_nop 0
	v_rcp_f32_e32 v12, v12
	v_rcp_f32_e32 v13, v13
	v_pk_mul_f32 v[2:3], v[2:3], v[10:11]
	v_med3_f32 v10, v16, s18, v236
	v_med3_f32 v11, v17, s18, v236
	v_pk_mul_f32 v[8:9], v[8:9], v[12:13]
	v_pk_mul_f32 v[12:13], v[6:7], s[86:87] op_sel_hi:[1,0]
	v_pk_fma_f32 v[10:11], v[10:11], 4.0, 4.0 op_sel_hi:[1,0,0]
	v_exp_f32_e32 v12, v12
	v_exp_f32_e32 v13, v13
	v_pk_mul_f32 v[8:9], v[8:9], v[10:11]
	v_med3_f32 v10, v14, s18, v236
	v_med3_f32 v11, v15, s18, v236
	v_pk_add_f32 v[12:13], v[12:13], 1.0 op_sel_hi:[1,0]
	v_pk_fma_f32 v[10:11], v[10:11], 4.0, 4.0 op_sel_hi:[1,0,0]
	v_rcp_f32_e32 v12, v12
	v_rcp_f32_e32 v13, v13
	v_pk_add_f32 v[16:17], v[44:45], v[72:73]
	v_pk_add_f32 v[14:15], v[46:47], v[74:75]
	v_pk_mul_f32 v[6:7], v[6:7], v[12:13]
	s_nop 0
	v_pk_mul_f32 v[6:7], v[6:7], v[10:11]
	v_mov_b32_e32 v10, v213
	v_cvt_pk_fp8_f32 v10, v4, v5
	v_pk_add_f32 v[4:5], v[32:33], v[68:69]
	v_mov_b32_e32 v11, v213
	v_min_f32_e32 v4, 0x40e00000, v4
	v_min_f32_e32 v5, 0x40e00000, v5
	v_pk_mul_f32 v[18:19], v[4:5], s[86:87] op_sel_hi:[1,0]
	v_cvt_pk_fp8_f32 v11, v8, v9
	v_exp_f32_e32 v18, v18
	v_exp_f32_e32 v19, v19
	v_cvt_pk_fp8_f32 v10, v2, v3 op_sel:[0,0,1]
	v_cvt_pk_fp8_f32 v11, v6, v7 op_sel:[0,0,1]
	v_add_co_u32_e32 v2, vcc, s8, v0
	v_pk_add_f32 v[18:19], v[18:19], 1.0 op_sel_hi:[1,0]
	s_nop 0
	v_addc_co_u32_e32 v3, vcc, 0, v1, vcc
	v_rcp_f32_e32 v18, v18
	v_rcp_f32_e32 v19, v19
	v_pk_add_f32 v[12:13], v[40:41], v[76:77]
	global_store_dwordx2 v[2:3], v[10:11], off
	v_pk_add_f32 v[2:3], v[34:35], v[70:71]
	v_med3_f32 v12, v12, s18, v236
	v_med3_f32 v13, v13, s18, v236
	v_pk_mul_f32 v[4:5], v[4:5], v[18:19]
	v_pk_fma_f32 v[12:13], v[12:13], 4.0, 4.0 op_sel_hi:[1,0,0]
	v_min_f32_e32 v2, 0x40e00000, v2
	v_min_f32_e32 v3, 0x40e00000, v3
	v_pk_mul_f32 v[4:5], v[4:5], v[12:13]
	v_pk_mul_f32 v[12:13], v[2:3], s[86:87] op_sel_hi:[1,0]
	v_pk_add_f32 v[8:9], v[36:37], v[64:65]
	v_exp_f32_e32 v12, v12
	v_exp_f32_e32 v13, v13
	v_min_f32_e32 v8, 0x40e00000, v8
	v_min_f32_e32 v9, 0x40e00000, v9
	v_pk_add_f32 v[6:7], v[38:39], v[66:67]
	v_pk_add_f32 v[12:13], v[12:13], 1.0 op_sel_hi:[1,0]
	v_min_f32_e32 v6, 0x40e00000, v6
	v_rcp_f32_e32 v12, v12
	v_rcp_f32_e32 v13, v13
	v_min_f32_e32 v7, 0x40e00000, v7
	v_pk_add_f32 v[10:11], v[42:43], v[78:79]
	s_mov_b64 s[8:9], -1
	v_pk_mul_f32 v[2:3], v[2:3], v[12:13]
	v_pk_mul_f32 v[12:13], v[8:9], s[86:87] op_sel_hi:[1,0]
	v_med3_f32 v10, v10, s18, v236
	v_exp_f32_e32 v12, v12
	v_exp_f32_e32 v13, v13
	v_med3_f32 v11, v11, s18, v236
	v_pk_fma_f32 v[10:11], v[10:11], 4.0, 4.0 op_sel_hi:[1,0,0]
	v_pk_add_f32 v[12:13], v[12:13], 1.0 op_sel_hi:[1,0]
	s_nop 0
	v_rcp_f32_e32 v12, v12
	v_rcp_f32_e32 v13, v13
	v_pk_mul_f32 v[2:3], v[2:3], v[10:11]
	v_med3_f32 v10, v16, s18, v236
	v_med3_f32 v11, v17, s18, v236
	v_pk_mul_f32 v[8:9], v[8:9], v[12:13]
	v_pk_mul_f32 v[12:13], v[6:7], s[86:87] op_sel_hi:[1,0]
	v_pk_fma_f32 v[10:11], v[10:11], 4.0, 4.0 op_sel_hi:[1,0,0]
	v_exp_f32_e32 v12, v12
	v_exp_f32_e32 v13, v13
	v_pk_mul_f32 v[8:9], v[8:9], v[10:11]
	v_med3_f32 v10, v14, s18, v236
	v_med3_f32 v11, v15, s18, v236
	v_pk_add_f32 v[12:13], v[12:13], 1.0 op_sel_hi:[1,0]
	v_pk_fma_f32 v[10:11], v[10:11], 4.0, 4.0 op_sel_hi:[1,0,0]
	v_rcp_f32_e32 v12, v12
	v_rcp_f32_e32 v13, v13
	v_pk_add_f32 v[16:17], v[44:45], v[56:57]
	v_pk_add_f32 v[14:15], v[46:47], v[58:59]
	v_pk_mul_f32 v[6:7], v[6:7], v[12:13]
	s_nop 0
	v_pk_mul_f32 v[6:7], v[6:7], v[10:11]
	v_mov_b32_e32 v10, v213
	v_cvt_pk_fp8_f32 v10, v4, v5
	v_pk_add_f32 v[4:5], v[32:33], v[52:53]
	v_mov_b32_e32 v11, v213
	v_min_f32_e32 v4, 0x40e00000, v4
	v_min_f32_e32 v5, 0x40e00000, v5
	v_pk_mul_f32 v[18:19], v[4:5], s[86:87] op_sel_hi:[1,0]
	v_cvt_pk_fp8_f32 v11, v8, v9
	v_exp_f32_e32 v18, v18
	v_exp_f32_e32 v19, v19
	v_cvt_pk_fp8_f32 v10, v2, v3 op_sel:[0,0,1]
	v_cvt_pk_fp8_f32 v11, v6, v7 op_sel:[0,0,1]
	v_add_co_u32_e32 v2, vcc, s77, v0
	v_pk_add_f32 v[18:19], v[18:19], 1.0 op_sel_hi:[1,0]
	s_nop 0
	v_addc_co_u32_e32 v3, vcc, 0, v1, vcc
	v_rcp_f32_e32 v18, v18
	v_rcp_f32_e32 v19, v19
	v_pk_add_f32 v[12:13], v[40:41], v[60:61]
	global_store_dwordx2 v[2:3], v[10:11], off
	v_pk_add_f32 v[2:3], v[34:35], v[54:55]
	v_med3_f32 v12, v12, s18, v236
	v_med3_f32 v13, v13, s18, v236
	v_pk_mul_f32 v[4:5], v[4:5], v[18:19]
	v_pk_fma_f32 v[12:13], v[12:13], 4.0, 4.0 op_sel_hi:[1,0,0]
	v_min_f32_e32 v2, 0x40e00000, v2
	v_min_f32_e32 v3, 0x40e00000, v3
	v_pk_mul_f32 v[4:5], v[4:5], v[12:13]
	v_pk_mul_f32 v[12:13], v[2:3], s[86:87] op_sel_hi:[1,0]
	v_pk_add_f32 v[8:9], v[36:37], v[48:49]
	v_exp_f32_e32 v12, v12
	v_exp_f32_e32 v13, v13
	v_min_f32_e32 v8, 0x40e00000, v8
	v_min_f32_e32 v9, 0x40e00000, v9
	v_pk_add_f32 v[6:7], v[38:39], v[50:51]
	v_pk_add_f32 v[12:13], v[12:13], 1.0 op_sel_hi:[1,0]
	v_min_f32_e32 v6, 0x40e00000, v6
	v_rcp_f32_e32 v12, v12
	v_rcp_f32_e32 v13, v13
	v_min_f32_e32 v7, 0x40e00000, v7
	v_pk_add_f32 v[10:11], v[42:43], v[62:63]
	v_add_co_u32_e32 v0, vcc, 0x2c000, v0
	v_pk_mul_f32 v[2:3], v[2:3], v[12:13]
	v_pk_mul_f32 v[12:13], v[8:9], s[86:87] op_sel_hi:[1,0]
	v_med3_f32 v10, v10, s18, v236
	v_exp_f32_e32 v12, v12
	v_exp_f32_e32 v13, v13
	v_med3_f32 v11, v11, s18, v236
	v_pk_fma_f32 v[10:11], v[10:11], 4.0, 4.0 op_sel_hi:[1,0,0]
	v_addc_co_u32_e32 v1, vcc, 0, v1, vcc
	v_pk_add_f32 v[12:13], v[12:13], 1.0 op_sel_hi:[1,0]
	v_pk_mul_f32 v[2:3], v[2:3], v[10:11]
	v_rcp_f32_e32 v12, v12
	v_rcp_f32_e32 v13, v13
	v_med3_f32 v10, v16, s18, v236
	v_med3_f32 v11, v17, s18, v236
	v_pk_fma_f32 v[10:11], v[10:11], 4.0, 4.0 op_sel_hi:[1,0,0]
	v_pk_mul_f32 v[8:9], v[8:9], v[12:13]
	v_pk_mul_f32 v[12:13], v[6:7], s[86:87] op_sel_hi:[1,0]
	v_pk_mul_f32 v[8:9], v[8:9], v[10:11]
	v_exp_f32_e32 v12, v12
	v_exp_f32_e32 v13, v13
	v_med3_f32 v10, v14, s18, v236
	v_med3_f32 v11, v15, s18, v236
	v_pk_fma_f32 v[10:11], v[10:11], 4.0, 4.0 op_sel_hi:[1,0,0]
	v_pk_add_f32 v[12:13], v[12:13], 1.0 op_sel_hi:[1,0]
	s_and_b64 vcc, exec, s[4:5]
	v_rcp_f32_e32 v12, v12
	v_rcp_f32_e32 v13, v13
	s_nop 0
	v_pk_mul_f32 v[6:7], v[6:7], v[12:13]
	s_nop 0
	v_pk_mul_f32 v[6:7], v[6:7], v[10:11]
	v_mov_b32_e32 v10, v213
	v_mov_b32_e32 v11, v213
	v_cvt_pk_fp8_f32 v10, v4, v5
	v_cvt_pk_fp8_f32 v11, v8, v9
	v_cvt_pk_fp8_f32 v10, v2, v3 op_sel:[0,0,1]
	v_cvt_pk_fp8_f32 v11, v6, v7 op_sel:[0,0,1]
	global_store_dwordx2 v[0:1], v[10:11], off
	s_cbranch_vccnz .LBB0_952
	s_and_b64 vcc, exec, s[2:3]
	s_nop 0
	s_nop 0
	s_nop 0
	s_nop 0
	s_nop 0
	s_nop 0
	s_nop 0
	s_nop 0
	s_nop 0
	s_nop 0
	s_nop 0
	s_nop 0
	s_nop 0
	s_nop 0
	s_nop 0
	s_nop 0
	s_nop 0
	s_nop 0
	s_nop 0
	s_nop 0
	s_nop 0
	s_nop 0
	s_nop 0
	s_nop 0
	s_nop 0
	s_nop 0
	s_nop 0
	s_nop 0
	s_nop 0
	s_nop 0
	s_nop 0
	s_cbranch_vccnz .LBB0_951
	s_barrier
	s_branch .LBB0_951

.LBB0_1064:
	v_pk_add_f32 v[2:3], v[32:33], v[172:173]
	v_pk_add_f32 v[6:7], v[36:37], v[168:169]
	v_mul_f32_e32 v2, 0x42000000, v2
	v_mul_f32_e32 v3, 0x42000000, v3
	v_mov_b32_e32 v8, v213
	v_cvt_pk_fp8_f32 v8, v2, v3
	v_mul_f32_e32 v2, 0x42000000, v6
	v_mul_f32_e32 v3, 0x42000000, v7
	v_mov_b32_e32 v9, v213
	v_cvt_pk_fp8_f32 v9, v2, v3
	v_pk_add_f32 v[2:3], v[32:33], v[164:165]
	v_pk_add_f32 v[0:1], v[34:35], v[174:175]
	v_pk_add_f32 v[6:7], v[36:37], v[160:161]
	v_mul_f32_e32 v2, 0x42000000, v2
	v_mul_f32_e32 v3, 0x42000000, v3
	v_mov_b32_e32 v10, v213
	v_pk_add_f32 v[4:5], v[38:39], v[170:171]
	v_mul_f32_e32 v0, 0x42000000, v0
	v_mul_f32_e32 v1, 0x42000000, v1
	v_cvt_pk_fp8_f32 v10, v2, v3
	v_mul_f32_e32 v2, 0x42000000, v6
	v_mul_f32_e32 v3, 0x42000000, v7
	v_mov_b32_e32 v6, v213
	v_cvt_pk_fp8_f32 v8, v0, v1 op_sel:[0,0,1]
	v_mul_f32_e32 v0, 0x42000000, v4
	v_mul_f32_e32 v1, 0x42000000, v5
	v_cvt_pk_fp8_f32 v6, v2, v3
	v_cvt_pk_fp8_f32 v9, v0, v1 op_sel:[0,0,1]
	v_pk_add_f32 v[0:1], v[34:35], v[166:167]
	v_pk_add_f32 v[4:5], v[38:39], v[162:163]
	v_mul_f32_e32 v0, 0x42000000, v0
	v_mul_f32_e32 v1, 0x42000000, v1
	v_cvt_pk_fp8_f32 v10, v0, v1 op_sel:[0,0,1]
	v_mul_f32_e32 v0, 0x42000000, v4
	v_mul_f32_e32 v1, 0x42000000, v5
	v_cvt_pk_fp8_f32 v6, v0, v1 op_sel:[0,0,1]
	v_cndmask_b32_e64 v0, v8, v10, s[4:5]
	ds_bpermute_b32 v7, v200, v0
	v_pk_add_f32 v[14:15], v[36:37], v[152:153]
	v_cndmask_b32_e64 v1, v9, v6, s[4:5]
	ds_bpermute_b32 v2, v200, v1
	v_mov_b32_e32 v16, v213
	s_waitcnt lgkmcnt(0)
	v_cndmask_b32_e64 v4, v10, v7, s[4:5]
	v_pk_add_f32 v[10:11], v[32:33], v[156:157]
	v_mov_b32_e32 v17, v213
	v_cndmask_b32_e64 v5, v6, v2, s[4:5]
	v_cndmask_b32_e64 v3, v2, v9, s[4:5]
	v_cndmask_b32_e64 v2, v7, v8, s[4:5]
	v_pk_add_f32 v[8:9], v[34:35], v[158:159]
	v_mul_f32_e32 v7, 0x42000000, v10
	v_mul_f32_e32 v10, 0x42000000, v11
	v_cvt_pk_fp8_f32 v16, v7, v10
	v_mul_f32_e32 v7, 0x42000000, v8
	v_mul_f32_e32 v8, 0x42000000, v9
	v_mul_f32_e32 v9, 0x42000000, v14
	v_mul_f32_e32 v10, 0x42000000, v15
	v_cvt_pk_fp8_f32 v17, v9, v10
	v_pk_add_f32 v[12:13], v[38:39], v[154:155]
	v_cvt_pk_fp8_f32 v16, v7, v8 op_sel:[0,0,1]
	v_mul_f32_e32 v7, 0x42000000, v12
	v_mul_f32_e32 v8, 0x42000000, v13
	v_pk_add_f32 v[10:11], v[32:33], v[148:149]
	v_cvt_pk_fp8_f32 v17, v7, v8 op_sel:[0,0,1]
	v_pk_add_f32 v[8:9], v[34:35], v[150:151]
	v_pk_add_f32 v[14:15], v[36:37], v[144:145]
	v_mul_f32_e32 v7, 0x42000000, v10
	v_mul_f32_e32 v10, 0x42000000, v11
	v_mov_b32_e32 v11, v213
	v_cvt_pk_fp8_f32 v11, v7, v10
	v_mul_f32_e32 v7, 0x42000000, v8
	v_mul_f32_e32 v8, 0x42000000, v9
	v_mul_f32_e32 v9, 0x42000000, v14
	v_mul_f32_e32 v10, 0x42000000, v15
	v_mov_b32_e32 v14, v213
	v_cvt_pk_fp8_f32 v14, v9, v10
	v_pk_add_f32 v[12:13], v[38:39], v[146:147]
	v_cvt_pk_fp8_f32 v11, v7, v8 op_sel:[0,0,1]
	v_mul_f32_e32 v7, 0x42000000, v12
	v_mul_f32_e32 v8, 0x42000000, v13
	v_cvt_pk_fp8_f32 v14, v7, v8 op_sel:[0,0,1]
	v_add_u32_e32 v18, s55, v198
	v_cndmask_b32_e64 v8, v16, v11, s[4:5]
	v_add_u32_e32 v6, v18, v201
	v_cndmask_b32_e64 v9, v17, v14, s[4:5]
	ds_bpermute_b32 v9, v200, v9
	ds_bpermute_b32 v8, v200, v8
	v_ashrrev_i32_e32 v7, 31, v6
	v_or_b32_e32 v0, s96, v203
	v_lshlrev_b64 v[6:7], 10, v[6:7]
	v_ashrrev_i32_e32 v1, 31, v0
	v_lshl_add_u64 v[6:7], s[16:17], 0, v[6:7]
	v_lshl_add_u64 v[6:7], v[6:7], 0, v[0:1]
	v_pk_add_f32 v[12:13], v[40:41], v[140:141]
	global_store_dwordx4 v[6:7], v[2:5], off
	v_mov_b32_e32 v19, v213
	v_mov_b32_e32 v20, v213
	s_waitcnt lgkmcnt(0)
	v_cndmask_b32_e64 v5, v14, v9, s[4:5]
	v_cndmask_b32_e64 v4, v11, v8, s[4:5]
	v_cndmask_b32_e64 v3, v9, v17, s[4:5]
	v_cndmask_b32_e64 v2, v8, v16, s[4:5]
	v_pk_add_f32 v[10:11], v[42:43], v[142:143]
	v_pk_add_f32 v[16:17], v[44:45], v[136:137]
	v_mul_f32_e32 v9, 0x42000000, v12
	v_mul_f32_e32 v12, 0x42000000, v13
	v_cvt_pk_fp8_f32 v19, v9, v12
	v_mul_f32_e32 v9, 0x42000000, v10
	v_mul_f32_e32 v10, 0x42000000, v11
	v_mul_f32_e32 v11, 0x42000000, v16
	v_mul_f32_e32 v12, 0x42000000, v17
	v_cvt_pk_fp8_f32 v20, v11, v12
	v_pk_add_f32 v[14:15], v[46:47], v[138:139]
	v_cvt_pk_fp8_f32 v19, v9, v10 op_sel:[0,0,1]
	v_mul_f32_e32 v9, 0x42000000, v14
	v_mul_f32_e32 v10, 0x42000000, v15
	v_pk_add_f32 v[12:13], v[40:41], v[132:133]
	v_cvt_pk_fp8_f32 v20, v9, v10 op_sel:[0,0,1]
	v_pk_add_f32 v[10:11], v[42:43], v[134:135]
	v_pk_add_f32 v[16:17], v[44:45], v[128:129]
	v_mul_f32_e32 v9, 0x42000000, v12
	v_mul_f32_e32 v12, 0x42000000, v13
	v_mov_b32_e32 v13, v213
	v_cvt_pk_fp8_f32 v13, v9, v12
	v_mul_f32_e32 v9, 0x42000000, v10
	v_mul_f32_e32 v10, 0x42000000, v11
	v_mul_f32_e32 v11, 0x42000000, v16
	v_mul_f32_e32 v12, 0x42000000, v17
	v_mov_b32_e32 v16, v213
	v_cvt_pk_fp8_f32 v16, v11, v12
	v_pk_add_f32 v[14:15], v[46:47], v[130:131]
	v_cvt_pk_fp8_f32 v13, v9, v10 op_sel:[0,0,1]
	v_mul_f32_e32 v9, 0x42000000, v14
	v_mul_f32_e32 v10, 0x42000000, v15
	v_cvt_pk_fp8_f32 v16, v9, v10 op_sel:[0,0,1]
	v_cndmask_b32_e64 v10, v19, v13, s[4:5]
	v_add_u32_e32 v8, v18, v202
	ds_bpermute_b32 v21, v200, v10
	v_cndmask_b32_e64 v11, v20, v16, s[4:5]
	v_ashrrev_i32_e32 v9, 31, v8
	ds_bpermute_b32 v11, v200, v11
	v_lshlrev_b64 v[8:9], 10, v[8:9]
	v_lshl_add_u64 v[8:9], s[16:17], 0, v[8:9]
	v_lshl_add_u64 v[8:9], v[8:9], 0, v[0:1]
	global_store_dwordx4 v[8:9], v[2:5], off
	v_mov_b32_e32 v22, v213
	v_pk_add_f32 v[14:15], v[46:47], v[114:115]
	s_waitcnt lgkmcnt(0)
	v_cndmask_b32_e64 v4, v13, v21, s[4:5]
	v_pk_add_f32 v[12:13], v[40:41], v[116:117]
	v_cndmask_b32_e64 v5, v16, v11, s[4:5]
	v_cndmask_b32_e64 v3, v11, v20, s[4:5]
	v_pk_add_f32 v[10:11], v[42:43], v[118:119]
	v_pk_add_f32 v[16:17], v[44:45], v[112:113]
	v_mul_f32_e32 v2, 0x42000000, v12
	v_mul_f32_e32 v12, 0x42000000, v13
	v_mov_b32_e32 v20, v213
	v_cvt_pk_fp8_f32 v20, v2, v12
	v_mul_f32_e32 v2, 0x42000000, v10
	v_mul_f32_e32 v10, 0x42000000, v11
	v_mul_f32_e32 v11, 0x42000000, v16
	v_mul_f32_e32 v12, 0x42000000, v17
	v_cvt_pk_fp8_f32 v22, v11, v12
	v_cvt_pk_fp8_f32 v20, v2, v10 op_sel:[0,0,1]
	v_mul_f32_e32 v2, 0x42000000, v14
	v_mul_f32_e32 v10, 0x42000000, v15
	v_pk_add_f32 v[12:13], v[40:41], v[100:101]
	v_pk_add_f32 v[16:17], v[44:45], v[96:97]
	v_cvt_pk_fp8_f32 v22, v2, v10 op_sel:[0,0,1]
	v_mul_f32_e32 v2, 0x42000000, v12
	v_mul_f32_e32 v12, 0x42000000, v13
	v_mul_f32_e32 v13, 0x42000000, v16
	v_mul_f32_e32 v16, 0x42000000, v17
	v_mov_b32_e32 v17, v213
	v_cvt_pk_fp8_f32 v17, v13, v16
	v_pk_add_f32 v[14:15], v[46:47], v[98:99]
	v_mov_b32_e32 v23, v213
	v_cvt_pk_fp8_f32 v23, v2, v12
	v_mul_f32_e32 v2, 0x42000000, v14
	v_mul_f32_e32 v12, 0x42000000, v15
	v_cvt_pk_fp8_f32 v17, v2, v12 op_sel:[0,0,1]
	v_pk_add_f32 v[10:11], v[42:43], v[102:103]
	v_pk_add_f32 v[12:13], v[36:37], v[120:121]
	v_mul_f32_e32 v2, 0x42000000, v10
	v_mul_f32_e32 v10, 0x42000000, v11
	v_cvt_pk_fp8_f32 v23, v2, v10 op_sel:[0,0,1]
	v_cndmask_b32_e64 v2, v22, v17, s[4:5]
	ds_bpermute_b32 v14, v200, v2
	v_cndmask_b32_e64 v2, v21, v19, s[4:5]
	global_store_dwordx4 v[6:7], v[2:5], off offset:128
	v_pk_add_f32 v[6:7], v[32:33], v[124:125]
	v_mov_b32_e32 v16, v213
	v_mul_f32_e32 v4, 0x42000000, v6
	v_mul_f32_e32 v6, 0x42000000, v7
	s_waitcnt lgkmcnt(0)
	v_cndmask_b32_e64 v5, v17, v14, s[4:5]
	v_cvt_pk_fp8_f32 v16, v4, v6
	v_mul_f32_e32 v4, 0x42000000, v12
	v_mul_f32_e32 v6, 0x42000000, v13
	v_mov_b32_e32 v17, v213
	v_cndmask_b32_e64 v2, v20, v23, s[4:5]
	v_cvt_pk_fp8_f32 v17, v4, v6
	v_pk_add_f32 v[6:7], v[32:33], v[108:109]
	ds_bpermute_b32 v15, v200, v2
	v_pk_add_f32 v[2:3], v[34:35], v[126:127]
	v_mul_f32_e32 v4, 0x42000000, v6
	v_mul_f32_e32 v6, 0x42000000, v7
	v_mov_b32_e32 v7, v213
	v_pk_add_f32 v[10:11], v[38:39], v[122:123]
	v_mul_f32_e32 v2, 0x42000000, v2
	v_mul_f32_e32 v3, 0x42000000, v3
	v_pk_add_f32 v[12:13], v[36:37], v[104:105]
	v_cvt_pk_fp8_f32 v7, v4, v6
	v_cvt_pk_fp8_f32 v16, v2, v3 op_sel:[0,0,1]
	v_mul_f32_e32 v2, 0x42000000, v10
	v_mul_f32_e32 v3, 0x42000000, v11
	v_mul_f32_e32 v4, 0x42000000, v12
	v_mul_f32_e32 v6, 0x42000000, v13
	v_mov_b32_e32 v12, v213
	v_cvt_pk_fp8_f32 v17, v2, v3 op_sel:[0,0,1]
	v_pk_add_f32 v[2:3], v[34:35], v[110:111]
	v_cvt_pk_fp8_f32 v12, v4, v6
	v_mul_f32_e32 v2, 0x42000000, v2
	v_mul_f32_e32 v3, 0x42000000, v3
	v_pk_add_f32 v[10:11], v[38:39], v[106:107]
	v_cvt_pk_fp8_f32 v7, v2, v3 op_sel:[0,0,1]
	v_mul_f32_e32 v2, 0x42000000, v10
	v_mul_f32_e32 v3, 0x42000000, v11
	v_cvt_pk_fp8_f32 v12, v2, v3 op_sel:[0,0,1]
	v_cndmask_b32_e64 v2, v16, v7, s[4:5]
	ds_bpermute_b32 v10, v200, v2
	s_waitcnt lgkmcnt(0)
	v_cndmask_b32_e64 v4, v23, v15, s[4:5]
	v_cndmask_b32_e64 v6, v17, v12, s[4:5]
	ds_bpermute_b32 v6, v200, v6
	v_cndmask_b32_e64 v3, v14, v22, s[4:5]
	v_cndmask_b32_e64 v2, v15, v20, s[4:5]
	global_store_dwordx4 v[8:9], v[2:5], off offset:128
	v_pk_add_f32 v[8:9], v[34:35], v[94:95]
	v_pk_add_f32 v[14:15], v[36:37], v[88:89]
	v_cndmask_b32_e64 v4, v7, v10, s[4:5]
	v_cndmask_b32_e64 v2, v10, v16, s[4:5]
	v_pk_add_f32 v[10:11], v[32:33], v[92:93]
	v_mov_b32_e32 v16, v213
	v_mul_f32_e32 v7, 0x42000000, v10
	v_mul_f32_e32 v10, 0x42000000, v11
	s_waitcnt lgkmcnt(0)
	v_cndmask_b32_e64 v3, v6, v17, s[4:5]
	v_cvt_pk_fp8_f32 v16, v7, v10
	v_mul_f32_e32 v7, 0x42000000, v8
	v_mul_f32_e32 v8, 0x42000000, v9
	v_mul_f32_e32 v9, 0x42000000, v14
	v_mul_f32_e32 v10, 0x42000000, v15
	v_mov_b32_e32 v17, v213
	v_cvt_pk_fp8_f32 v17, v9, v10
	v_cndmask_b32_e64 v5, v12, v6, s[4:5]
	v_pk_add_f32 v[12:13], v[38:39], v[90:91]
	v_cvt_pk_fp8_f32 v16, v7, v8 op_sel:[0,0,1]
	v_mul_f32_e32 v7, 0x42000000, v12
	v_mul_f32_e32 v8, 0x42000000, v13
	v_pk_add_f32 v[10:11], v[32:33], v[84:85]
	v_cvt_pk_fp8_f32 v17, v7, v8 op_sel:[0,0,1]
	v_pk_add_f32 v[8:9], v[34:35], v[86:87]
	v_pk_add_f32 v[14:15], v[36:37], v[80:81]
	v_mul_f32_e32 v7, 0x42000000, v10
	v_mul_f32_e32 v10, 0x42000000, v11
	v_mov_b32_e32 v11, v213
	v_cvt_pk_fp8_f32 v11, v7, v10
	v_mul_f32_e32 v7, 0x42000000, v8
	v_mul_f32_e32 v8, 0x42000000, v9
	v_mul_f32_e32 v9, 0x42000000, v14
	v_mul_f32_e32 v10, 0x42000000, v15
	v_mov_b32_e32 v14, v213
	v_cvt_pk_fp8_f32 v14, v9, v10
	v_pk_add_f32 v[12:13], v[38:39], v[82:83]
	v_cvt_pk_fp8_f32 v11, v7, v8 op_sel:[0,0,1]
	v_mul_f32_e32 v7, 0x42000000, v12
	v_mul_f32_e32 v8, 0x42000000, v13
	v_cvt_pk_fp8_f32 v14, v7, v8 op_sel:[0,0,1]
	v_add_u32_e32 v18, 0x80, v18
	v_cndmask_b32_e64 v8, v16, v11, s[4:5]
	v_add_u32_e32 v6, v18, v201
	v_cndmask_b32_e64 v9, v17, v14, s[4:5]
	ds_bpermute_b32 v9, v200, v9
	ds_bpermute_b32 v8, v200, v8
	v_ashrrev_i32_e32 v7, 31, v6
	v_lshlrev_b64 v[6:7], 10, v[6:7]
	v_lshl_add_u64 v[6:7], s[16:17], 0, v[6:7]
	v_lshl_add_u64 v[6:7], v[6:7], 0, v[0:1]
	v_pk_add_f32 v[12:13], v[40:41], v[76:77]
	global_store_dwordx4 v[6:7], v[2:5], off
	v_mul_f32_e32 v12, 0x42000000, v12
	v_mul_f32_e32 v13, 0x42000000, v13
	s_waitcnt lgkmcnt(0)
	v_cndmask_b32_e64 v4, v11, v8, s[4:5]
	v_cndmask_b32_e64 v3, v9, v17, s[4:5]
	v_cndmask_b32_e64 v2, v8, v16, s[4:5]
	v_add_u32_e32 v8, v18, v202
	v_pk_add_f32 v[16:17], v[44:45], v[72:73]
	v_mov_b32_e32 v18, v213
	v_cvt_pk_fp8_f32 v18, v12, v13
	v_mul_f32_e32 v12, 0x42000000, v16
	v_mul_f32_e32 v13, 0x42000000, v17
	v_mov_b32_e32 v19, v213
	v_cvt_pk_fp8_f32 v19, v12, v13
	v_pk_add_f32 v[12:13], v[40:41], v[68:69]
	v_pk_add_f32 v[10:11], v[42:43], v[78:79]
	v_pk_add_f32 v[16:17], v[44:45], v[64:65]
	v_mul_f32_e32 v12, 0x42000000, v12
	v_mul_f32_e32 v13, 0x42000000, v13
	v_mov_b32_e32 v20, v213
	v_cndmask_b32_e64 v5, v14, v9, s[4:5]
	v_pk_add_f32 v[14:15], v[46:47], v[74:75]
	v_mul_f32_e32 v10, 0x42000000, v10
	v_mul_f32_e32 v11, 0x42000000, v11
	v_cvt_pk_fp8_f32 v20, v12, v13
	v_mul_f32_e32 v12, 0x42000000, v16
	v_mul_f32_e32 v13, 0x42000000, v17
	v_mov_b32_e32 v16, v213
	v_cvt_pk_fp8_f32 v18, v10, v11 op_sel:[0,0,1]
	v_mul_f32_e32 v10, 0x42000000, v14
	v_mul_f32_e32 v11, 0x42000000, v15
	v_cvt_pk_fp8_f32 v16, v12, v13
	v_ashrrev_i32_e32 v9, 31, v8
	v_cvt_pk_fp8_f32 v19, v10, v11 op_sel:[0,0,1]
	v_pk_add_f32 v[10:11], v[42:43], v[70:71]
	v_lshlrev_b64 v[8:9], 10, v[8:9]
	v_pk_add_f32 v[14:15], v[46:47], v[66:67]
	v_mul_f32_e32 v10, 0x42000000, v10
	v_mul_f32_e32 v11, 0x42000000, v11
	v_lshl_add_u64 v[8:9], s[16:17], 0, v[8:9]
	v_cvt_pk_fp8_f32 v20, v10, v11 op_sel:[0,0,1]
	v_mul_f32_e32 v10, 0x42000000, v14
	v_mul_f32_e32 v11, 0x42000000, v15
	v_cvt_pk_fp8_f32 v16, v10, v11 op_sel:[0,0,1]
	v_lshl_add_u64 v[8:9], v[8:9], 0, v[0:1]
	global_store_dwordx4 v[8:9], v[2:5], off
	v_pk_add_f32 v[10:11], v[44:45], v[56:57]
	v_mov_b32_e32 v14, v213
	v_pk_add_f32 v[2:3], v[40:41], v[60:61]
	v_mov_b32_e32 v15, v213
	v_mul_f32_e32 v2, 0x42000000, v2
	v_mul_f32_e32 v3, 0x42000000, v3
	v_cvt_pk_fp8_f32 v14, v2, v3
	v_mul_f32_e32 v2, 0x42000000, v10
	v_mul_f32_e32 v3, 0x42000000, v11
	v_cndmask_b32_e64 v0, v18, v20, s[4:5]
	v_cndmask_b32_e64 v1, v19, v16, s[4:5]
	v_cvt_pk_fp8_f32 v15, v2, v3
	v_pk_add_f32 v[2:3], v[40:41], v[52:53]
	ds_bpermute_b32 v12, v200, v0
	ds_bpermute_b32 v13, v200, v1
	v_pk_add_f32 v[0:1], v[42:43], v[62:63]
	v_pk_add_f32 v[10:11], v[44:45], v[48:49]
	v_mul_f32_e32 v2, 0x42000000, v2
	v_mul_f32_e32 v3, 0x42000000, v3
	v_mov_b32_e32 v17, v213
	v_pk_add_f32 v[4:5], v[46:47], v[58:59]
	v_mul_f32_e32 v0, 0x42000000, v0
	v_mul_f32_e32 v1, 0x42000000, v1
	v_cvt_pk_fp8_f32 v17, v2, v3
	v_mul_f32_e32 v2, 0x42000000, v10
	v_mul_f32_e32 v3, 0x42000000, v11
	v_mov_b32_e32 v10, v213
	v_cvt_pk_fp8_f32 v14, v0, v1 op_sel:[0,0,1]
	v_mul_f32_e32 v0, 0x42000000, v4
	v_mul_f32_e32 v1, 0x42000000, v5
	v_cvt_pk_fp8_f32 v10, v2, v3
	v_cvt_pk_fp8_f32 v15, v0, v1 op_sel:[0,0,1]
	v_pk_add_f32 v[0:1], v[42:43], v[54:55]
	v_pk_add_f32 v[4:5], v[46:47], v[50:51]
	v_mul_f32_e32 v0, 0x42000000, v0
	v_mul_f32_e32 v1, 0x42000000, v1
	v_cvt_pk_fp8_f32 v17, v0, v1 op_sel:[0,0,1]
	v_mul_f32_e32 v0, 0x42000000, v4
	v_mul_f32_e32 v1, 0x42000000, v5
	v_cvt_pk_fp8_f32 v10, v0, v1 op_sel:[0,0,1]
	v_cndmask_b32_e64 v0, v14, v17, s[4:5]
	ds_bpermute_b32 v5, v200, v0
	s_waitcnt lgkmcnt(0)
	v_cndmask_b32_e64 v3, v16, v13, s[4:5]
	v_cndmask_b32_e64 v1, v15, v10, s[4:5]
	ds_bpermute_b32 v4, v200, v1
	v_cndmask_b32_e64 v2, v20, v12, s[4:5]
	v_cndmask_b32_e64 v1, v13, v19, s[4:5]
	v_cndmask_b32_e64 v0, v12, v18, s[4:5]
	global_store_dwordx4 v[6:7], v[0:3], off offset:128
	s_and_b64 vcc, exec, s[6:7]
	s_mov_b64 s[6:7], -1
	s_waitcnt lgkmcnt(0)
	v_cndmask_b32_e64 v3, v10, v4, s[4:5]
	v_cndmask_b32_e64 v2, v17, v5, s[4:5]
	v_cndmask_b32_e64 v1, v4, v15, s[4:5]
	v_cndmask_b32_e64 v0, v5, v14, s[4:5]
	v_mov_b32_e32 v251, v230
	v_mov_b32_e32 v252, v195
	global_store_dwordx4 v[8:9], v[0:3], off offset:128
	s_cbranch_vccnz .LBB0_1050
	s_and_b64 vcc, exec, s[2:3]
	s_nop 0
	s_nop 0
	s_nop 0
	s_nop 0
	s_nop 0
	s_nop 0
	s_nop 0
	s_nop 0
	s_nop 0
	s_nop 0
	s_nop 0
	s_nop 0
	s_nop 0
	s_nop 0
	s_nop 0
	s_nop 0
	s_nop 0
	s_nop 0
	s_nop 0
	s_nop 0
	s_nop 0
	s_nop 0
	s_nop 0
	s_nop 0
	s_nop 0
	s_nop 0
	s_nop 0
	s_nop 0
	s_nop 0
	s_nop 0
	s_nop 0
	s_cbranch_vccnz .LBB0_1049
	s_barrier
	s_branch .LBB0_1049
